# PLE projection GEMM (K=256 -> MIX32) moved from phase 12 into phase 9 as a second GEMM on the 128 workgroups idle in the FFN gate/up GEMM's half-empty last round
# speedup vs baseline: 1.0079x; 1.0017x over previous
.LBB0_678:
	s_mov_b64 s[4:5], -1
	s_cmp_lt_i32 s53, 10
	s_cbranch_scc1 .LBB0_694
	s_cmp_lt_i32 s53, 12
	s_cbranch_scc1 .LBB0_689
	v_readlane_b32 s2, v255, 47
	s_mov_b64 s[10:11], 0
	s_cmp_eq_u32 s53, 12
	s_mov_b64 s[8:9], 0
	s_mov_b32 s50, s66
	s_mov_b32 s18, s2
	s_mov_b32 s20, s69
	s_mov_b32 s51, s72
	s_mov_b64 s[14:15], s[90:91]
	s_mov_b64 s[16:17], s[92:93]
	v_readlane_b32 s52, v255, 48
	s_cbranch_scc0 .LBB0_689
	s_cmp_lg_u32 s48, 0
	s_cbranch_scc1 .LBB0_689
	s_branch .Lple_q12
	s_mov_b64 s[8:9], -1
	s_mov_b64 s[12:13], 0
	s_cmp_lt_i32 s48, 2
	s_mov_b64 s[14:15], 0
	s_cbranch_scc1 .LBB0_683
	s_cmp_lg_u32 s48, 2
	s_mov_b64 s[8:9], 0
	s_cselect_b64 s[14:15], -1, 0

.Lple_q12:
	s_waitcnt lgkmcnt(0)
	s_add_u32 s14, s6, 0x9640000
	s_addc_u32 s15, s7, 0
	s_add_u32 s16, s6, 0x8400000
	s_addc_u32 s17, s7, 0
	s_mov_b64 s[12:13], 0
	s_movk_i32 s18, 0x800
	s_mov_b32 s50, 10
	s_mov_b64 s[8:9], -1
	s_movk_i32 s20, 0x800
	s_movk_i32 s51, 0x800
	s_movk_i32 s52, 0x800

.LBB0_694:
	s_andn2_b64 vcc, exec, s[10:11]
	s_cbranch_vccnz .LBB0_702
	s_cmp_gt_i32 s53, 8
	s_mov_b64 s[10:11], -1
	s_cbranch_scc0 .LBB0_697
	v_readlane_b32 s2, v255, 47
	s_mov_b64 s[4:5], -1
	s_mov_b64 s[10:11], 0
	s_cmp_lg_u32 s48, 0
	s_mov_b64 s[8:9], 0
	s_mov_b32 s50, s66
	s_mov_b32 s18, s2
	s_mov_b32 s20, s69
	s_mov_b32 s51, s72
	s_mov_b64 s[14:15], s[90:91]
	s_mov_b64 s[16:17], s[92:93]
	v_readlane_b32 s52, v255, 48
	s_cbranch_scc0 .LBB0_703
	s_cmp_eq_u32 s48, 1
	s_cbranch_scc1 .Lple_q9

.Lple_q9:
	v_readlane_b32 s8, v255, 37
	v_readlane_b32 s9, v255, 38
	s_waitcnt lgkmcnt(0)
	s_add_u32 s2, s6, s8
	s_addc_u32 s8, s7, s9
	s_add_u32 s14, s2, 0x8e40000
	s_addc_u32 s15, s8, 0
	s_add_u32 s16, s6, 0x8c00000
	s_addc_u32 s17, s7, 0
	s_movk_i32 s52, 0x800
	s_movk_i32 s18, 0x100
	s_mov_b32 s50, 3
	s_mov_b64 s[4:5], -1
	s_mov_b64 s[8:9], -1
	s_movk_i32 s20, 0x100
	s_movk_i32 s51, 0x100
	s_branch .LBB0_702

.LBB0_735:
	s_cmp_lg_u32 s53, 9
	s_cbranch_scc1 .Lple_so
	s_cmp_lg_u32 s48, 1
	s_cbranch_scc1 .Lple_so
	s_movk_i32 s28, 0x80
	s_sub_i32 s42, s73, 0x80
